# phase 2 rms512 row normalisation: 8 rows in flight per wave (loads up front, butterfly hops batched per wait), same per-row arithmetic
# baseline (speedup 1.0000x reference)
; __device__ __forceinline__ float bflo(unsigned w) { return __uint_as_float(w << 16); }
; __device__ __forceinline__ float bfhi(unsigned w) { return __uint_as_float(w & 0xffff0000u); }
; __device__ __forceinline__ float wave_sum(float v) {
; #pragma unroll
;     for (int o = 1; o < 64; o <<= 1) v += __shfl_xor(v, o);
;     return v;
; }
; __device__ __forceinline__ void rms512_inplace(bf16* __restrict__ A, int gw, int NGW, int lane) {
;     for (int m = gw; m < S_; m += NGW) {
;         v4u* p = (v4u*)(A + (size_t)m * 512) + lane; const v4u w = *p;
;         float f[8] = {bflo(w.x), bfhi(w.x), bflo(w.y), bfhi(w.y), bflo(w.z), bfhi(w.z), bflo(w.w), bfhi(w.w)}; float s = 0.f;
; #pragma unroll
;         for (int e = 0; e < 8; ++e) s += f[e] * f[e];
.Lrms_q_batch:
	s_mul_i32 s14, s10, 7
	s_add_i32 s14, s14, s11
	s_cmpk_lt_i32 s14, 0x4000
	s_cbranch_scc0 .LBB0_1061
	v_mov_b32_e32 v116, v4
	v_mov_b32_e32 v117, v5
	v_lshl_add_u64 v[118:119], v[116:117], 0, s[12:13]
	v_lshl_add_u64 v[120:121], v[118:119], 0, s[12:13]
	v_lshl_add_u64 v[122:123], v[120:121], 0, s[12:13]
	v_lshl_add_u64 v[124:125], v[122:123], 0, s[12:13]
	v_lshl_add_u64 v[126:127], v[124:125], 0, s[12:13]
	v_lshl_add_u64 v[128:129], v[126:127], 0, s[12:13]
	v_lshl_add_u64 v[130:131], v[128:129], 0, s[12:13]
	global_load_dwordx4 v[32:35], v[116:117], off
	global_load_dwordx4 v[40:43], v[118:119], off
	global_load_dwordx4 v[48:51], v[120:121], off
	global_load_dwordx4 v[56:59], v[122:123], off
	global_load_dwordx4 v[64:67], v[124:125], off
	global_load_dwordx4 v[72:75], v[126:127], off
	global_load_dwordx4 v[80:83], v[128:129], off
	global_load_dwordx4 v[88:91], v[130:131], off
	s_waitcnt vmcnt(7)
	v_lshlrev_b32_e32 v36, 16, v32
	v_and_b32_e32 v32, 0xffff0000, v32
	v_mul_f32_e32 v100, v32, v32
	v_lshlrev_b32_e32 v37, 16, v33
	v_fmac_f32_e32 v100, v36, v36
	v_and_b32_e32 v33, 0xffff0000, v33
	v_fmac_f32_e32 v100, v37, v37
	v_lshlrev_b32_e32 v38, 16, v34
	v_fmac_f32_e32 v100, v33, v33
	v_and_b32_e32 v34, 0xffff0000, v34
	v_fmac_f32_e32 v100, v38, v38
	v_lshlrev_b32_e32 v39, 16, v35
	v_fmac_f32_e32 v100, v34, v34
	v_and_b32_e32 v35, 0xffff0000, v35
	v_fmac_f32_e32 v100, v39, v39
	v_fmac_f32_e32 v100, v35, v35
	s_waitcnt vmcnt(6)
	v_lshlrev_b32_e32 v44, 16, v40
	v_and_b32_e32 v40, 0xffff0000, v40
	v_mul_f32_e32 v101, v40, v40
	v_lshlrev_b32_e32 v45, 16, v41
	v_fmac_f32_e32 v101, v44, v44
	v_and_b32_e32 v41, 0xffff0000, v41
	v_fmac_f32_e32 v101, v45, v45
	v_lshlrev_b32_e32 v46, 16, v42
	v_fmac_f32_e32 v101, v41, v41
	v_and_b32_e32 v42, 0xffff0000, v42
	v_fmac_f32_e32 v101, v46, v46
	v_lshlrev_b32_e32 v47, 16, v43
	v_fmac_f32_e32 v101, v42, v42
	v_and_b32_e32 v43, 0xffff0000, v43
	v_fmac_f32_e32 v101, v47, v47
	v_fmac_f32_e32 v101, v43, v43
	s_waitcnt vmcnt(5)
	v_lshlrev_b32_e32 v52, 16, v48
	v_and_b32_e32 v48, 0xffff0000, v48
	v_mul_f32_e32 v102, v48, v48
	v_lshlrev_b32_e32 v53, 16, v49
	v_fmac_f32_e32 v102, v52, v52
	v_and_b32_e32 v49, 0xffff0000, v49
	v_fmac_f32_e32 v102, v53, v53
	v_lshlrev_b32_e32 v54, 16, v50
	v_fmac_f32_e32 v102, v49, v49
	v_and_b32_e32 v50, 0xffff0000, v50
	v_fmac_f32_e32 v102, v54, v54
	v_lshlrev_b32_e32 v55, 16, v51
	v_fmac_f32_e32 v102, v50, v50
	v_and_b32_e32 v51, 0xffff0000, v51
	v_fmac_f32_e32 v102, v55, v55
	v_fmac_f32_e32 v102, v51, v51
	s_waitcnt vmcnt(4)
	v_lshlrev_b32_e32 v60, 16, v56
	v_and_b32_e32 v56, 0xffff0000, v56
	v_mul_f32_e32 v103, v56, v56
	v_lshlrev_b32_e32 v61, 16, v57
	v_fmac_f32_e32 v103, v60, v60
	v_and_b32_e32 v57, 0xffff0000, v57
	v_fmac_f32_e32 v103, v61, v61
	v_lshlrev_b32_e32 v62, 16, v58
	v_fmac_f32_e32 v103, v57, v57
	v_and_b32_e32 v58, 0xffff0000, v58
	v_fmac_f32_e32 v103, v62, v62
	v_lshlrev_b32_e32 v63, 16, v59
	v_fmac_f32_e32 v103, v58, v58
	v_and_b32_e32 v59, 0xffff0000, v59
	v_fmac_f32_e32 v103, v63, v63
	v_fmac_f32_e32 v103, v59, v59
	s_waitcnt vmcnt(3)
	v_lshlrev_b32_e32 v68, 16, v64
	v_and_b32_e32 v64, 0xffff0000, v64
	v_mul_f32_e32 v104, v64, v64
	v_lshlrev_b32_e32 v69, 16, v65
	v_fmac_f32_e32 v104, v68, v68
	v_and_b32_e32 v65, 0xffff0000, v65
	v_fmac_f32_e32 v104, v69, v69
	v_lshlrev_b32_e32 v70, 16, v66
	v_fmac_f32_e32 v104, v65, v65
	v_and_b32_e32 v66, 0xffff0000, v66
	v_fmac_f32_e32 v104, v70, v70
	v_lshlrev_b32_e32 v71, 16, v67
	v_fmac_f32_e32 v104, v66, v66
	v_and_b32_e32 v67, 0xffff0000, v67
	v_fmac_f32_e32 v104, v71, v71
	v_fmac_f32_e32 v104, v67, v67
	s_waitcnt vmcnt(2)
	v_lshlrev_b32_e32 v76, 16, v72
	v_and_b32_e32 v72, 0xffff0000, v72
	v_mul_f32_e32 v105, v72, v72
	v_lshlrev_b32_e32 v77, 16, v73
	v_fmac_f32_e32 v105, v76, v76
	v_and_b32_e32 v73, 0xffff0000, v73
	v_fmac_f32_e32 v105, v77, v77
	v_lshlrev_b32_e32 v78, 16, v74
	v_fmac_f32_e32 v105, v73, v73
	v_and_b32_e32 v74, 0xffff0000, v74
	v_fmac_f32_e32 v105, v78, v78
	v_lshlrev_b32_e32 v79, 16, v75
	v_fmac_f32_e32 v105, v74, v74
	v_and_b32_e32 v75, 0xffff0000, v75
	v_fmac_f32_e32 v105, v79, v79
	v_fmac_f32_e32 v105, v75, v75
	s_waitcnt vmcnt(1)
	v_lshlrev_b32_e32 v84, 16, v80
	v_and_b32_e32 v80, 0xffff0000, v80
	v_mul_f32_e32 v106, v80, v80
	v_lshlrev_b32_e32 v85, 16, v81
	v_fmac_f32_e32 v106, v84, v84
	v_and_b32_e32 v81, 0xffff0000, v81
	v_fmac_f32_e32 v106, v85, v85
	v_lshlrev_b32_e32 v86, 16, v82
	v_fmac_f32_e32 v106, v81, v81
	v_and_b32_e32 v82, 0xffff0000, v82
	v_fmac_f32_e32 v106, v86, v86
	v_lshlrev_b32_e32 v87, 16, v83
	v_fmac_f32_e32 v106, v82, v82
	v_and_b32_e32 v83, 0xffff0000, v83
	v_fmac_f32_e32 v106, v87, v87
	v_fmac_f32_e32 v106, v83, v83
	s_waitcnt vmcnt(0)
	v_lshlrev_b32_e32 v92, 16, v88
	v_and_b32_e32 v88, 0xffff0000, v88
	v_mul_f32_e32 v107, v88, v88
	v_lshlrev_b32_e32 v93, 16, v89
	v_fmac_f32_e32 v107, v92, v92
	v_and_b32_e32 v89, 0xffff0000, v89
	v_fmac_f32_e32 v107, v93, v93
	v_lshlrev_b32_e32 v94, 16, v90
	v_fmac_f32_e32 v107, v89, v89
	v_and_b32_e32 v90, 0xffff0000, v90
	v_fmac_f32_e32 v107, v94, v94
	v_lshlrev_b32_e32 v95, 16, v91
	v_fmac_f32_e32 v107, v90, v90
	v_and_b32_e32 v91, 0xffff0000, v91
	v_fmac_f32_e32 v107, v95, v95
	v_fmac_f32_e32 v107, v91, v91
	ds_bpermute_b32 v108, v0, v100
	ds_bpermute_b32 v109, v0, v101
	ds_bpermute_b32 v110, v0, v102
	ds_bpermute_b32 v111, v0, v103
	ds_bpermute_b32 v112, v0, v104
	ds_bpermute_b32 v113, v0, v105
	ds_bpermute_b32 v114, v0, v106
	ds_bpermute_b32 v115, v0, v107
	s_waitcnt lgkmcnt(0)
; __device__ __forceinline__ unsigned pk2(float lo, float hi) { unsigned r; asm volatile("v_cvt_pk_bf16_f32 %0, %1, %2" : "=v"(r) : "v"(lo), "v"(hi)); return r; }
; __device__ __forceinline__ float wave_sum(float v) {
; #pragma unroll
;     for (int o = 1; o < 64; o <<= 1) v += __shfl_xor(v, o);
;     return v;
; }
; __device__ __forceinline__ void rms512_inplace(bf16* __restrict__ A, int gw, int NGW, int lane) {
;     ...
;         const float rstd = 1.f / sqrtf(wave_sum(s) * (1.f / 512) + EPS_);
;         v4u o; o.x = pk2(f[0] * rstd, f[1] * rstd); o.y = pk2(f[2] * rstd, f[3] * rstd); o.z = pk2(f[4] * rstd, f[5] * rstd); o.w = pk2(f[6] * rstd, f[7] * rstd); *p = o;
	v_add_f32_e32 v100, v100, v108
	v_add_f32_e32 v101, v101, v109
	v_add_f32_e32 v102, v102, v110
	v_add_f32_e32 v103, v103, v111
	v_add_f32_e32 v104, v104, v112
	v_add_f32_e32 v105, v105, v113
	v_add_f32_e32 v106, v106, v114
	v_add_f32_e32 v107, v107, v115
	ds_bpermute_b32 v108, v6, v100
	ds_bpermute_b32 v109, v6, v101
	ds_bpermute_b32 v110, v6, v102
	ds_bpermute_b32 v111, v6, v103
	ds_bpermute_b32 v112, v6, v104
	ds_bpermute_b32 v113, v6, v105
	ds_bpermute_b32 v114, v6, v106
	ds_bpermute_b32 v115, v6, v107
	s_waitcnt lgkmcnt(0)
	v_add_f32_e32 v100, v100, v108
	v_add_f32_e32 v101, v101, v109
	v_add_f32_e32 v102, v102, v110
	v_add_f32_e32 v103, v103, v111
	v_add_f32_e32 v104, v104, v112
	v_add_f32_e32 v105, v105, v113
	v_add_f32_e32 v106, v106, v114
	v_add_f32_e32 v107, v107, v115
	ds_bpermute_b32 v108, v7, v100
	ds_bpermute_b32 v109, v7, v101
	ds_bpermute_b32 v110, v7, v102
	ds_bpermute_b32 v111, v7, v103
	ds_bpermute_b32 v112, v7, v104
	ds_bpermute_b32 v113, v7, v105
	ds_bpermute_b32 v114, v7, v106
	ds_bpermute_b32 v115, v7, v107
	s_waitcnt lgkmcnt(0)
	v_add_f32_e32 v100, v100, v108
	v_add_f32_e32 v101, v101, v109
	v_add_f32_e32 v102, v102, v110
	v_add_f32_e32 v103, v103, v111
	v_add_f32_e32 v104, v104, v112
	v_add_f32_e32 v105, v105, v113
	v_add_f32_e32 v106, v106, v114
	v_add_f32_e32 v107, v107, v115
	ds_bpermute_b32 v108, v8, v100
	ds_bpermute_b32 v109, v8, v101
	ds_bpermute_b32 v110, v8, v102
	ds_bpermute_b32 v111, v8, v103
	ds_bpermute_b32 v112, v8, v104
	ds_bpermute_b32 v113, v8, v105
	ds_bpermute_b32 v114, v8, v106
	ds_bpermute_b32 v115, v8, v107
	s_waitcnt lgkmcnt(0)
	v_add_f32_e32 v100, v100, v108
	v_add_f32_e32 v101, v101, v109
	v_add_f32_e32 v102, v102, v110
	v_add_f32_e32 v103, v103, v111
	v_add_f32_e32 v104, v104, v112
	v_add_f32_e32 v105, v105, v113
	v_add_f32_e32 v106, v106, v114
	v_add_f32_e32 v107, v107, v115
	ds_bpermute_b32 v108, v9, v100
	ds_bpermute_b32 v109, v9, v101
	ds_bpermute_b32 v110, v9, v102
	ds_bpermute_b32 v111, v9, v103
	ds_bpermute_b32 v112, v9, v104
	ds_bpermute_b32 v113, v9, v105
	ds_bpermute_b32 v114, v9, v106
	ds_bpermute_b32 v115, v9, v107
	s_waitcnt lgkmcnt(0)
	v_add_f32_e32 v100, v100, v108
	v_add_f32_e32 v101, v101, v109
	v_add_f32_e32 v102, v102, v110
	v_add_f32_e32 v103, v103, v111
	v_add_f32_e32 v104, v104, v112
	v_add_f32_e32 v105, v105, v113
	v_add_f32_e32 v106, v106, v114
	v_add_f32_e32 v107, v107, v115
	ds_bpermute_b32 v108, v10, v100
	ds_bpermute_b32 v109, v10, v101
	ds_bpermute_b32 v110, v10, v102
	ds_bpermute_b32 v111, v10, v103
	ds_bpermute_b32 v112, v10, v104
	ds_bpermute_b32 v113, v10, v105
	ds_bpermute_b32 v114, v10, v106
	ds_bpermute_b32 v115, v10, v107
	s_waitcnt lgkmcnt(0)
	v_add_f32_e32 v100, v100, v108
	v_add_f32_e32 v101, v101, v109
	v_add_f32_e32 v102, v102, v110
	v_add_f32_e32 v103, v103, v111
	v_add_f32_e32 v104, v104, v112
	v_add_f32_e32 v105, v105, v113
	v_add_f32_e32 v106, v106, v114
	v_add_f32_e32 v107, v107, v115
	v_fmamk_f32 v100, v100, 0x3b000000, v190
	v_mul_f32_e32 v132, 0x4f800000, v100
	v_cmp_gt_f32_e32 vcc, s73, v100
	s_nop 1
	v_cndmask_b32_e32 v100, v100, v132, vcc
	v_sqrt_f32_e32 v132, v100
	s_nop 0
	v_add_u32_e32 v133, -1, v132
	v_add_u32_e32 v134, 1, v132
	v_fma_f32 v135, -v133, v132, v100
	v_fma_f32 v136, -v134, v132, v100
	v_cmp_ge_f32_e64 s[40:41], 0, v135
	s_nop 1
	v_cndmask_b32_e64 v132, v132, v133, s[40:41]
	v_cmp_lt_f32_e64 s[40:41], 0, v136
	s_nop 1
	v_cndmask_b32_e64 v132, v132, v134, s[40:41]
	v_mul_f32_e32 v133, 0x37800000, v132
	v_cndmask_b32_e32 v132, v132, v133, vcc
	v_cmp_class_f32_e32 vcc, v100, v191
	s_nop 1
	v_cndmask_b32_e32 v100, v132, v100, vcc
	v_div_scale_f32 v132, s[14:15], v100, v100, 1.0
	v_rcp_f32_e32 v133, v132
	v_div_scale_f32 v134, vcc, 1.0, v100, 1.0
	v_fma_f32 v135, -v132, v133, 1.0
	v_fmac_f32_e32 v133, v135, v133
	v_mul_f32_e32 v135, v134, v133
	v_fma_f32 v136, -v132, v135, v134
	v_fmac_f32_e32 v135, v136, v133
	v_fma_f32 v132, -v132, v135, v134
	v_div_fmas_f32 v132, v132, v133, v135
	v_div_fixup_f32 v100, v132, v100, 1.0
	v_mul_f32_e32 v36, v100, v36
	v_mul_f32_e32 v32, v100, v32
	v_mul_f32_e32 v37, v100, v37
	v_mul_f32_e32 v33, v100, v33
	v_mul_f32_e32 v38, v100, v38
	v_mul_f32_e32 v34, v100, v34
	v_mul_f32_e32 v39, v100, v39
	v_mul_f32_e32 v35, v100, v35
	v_cvt_pk_bf16_f32 v32, v36, v32
	v_cvt_pk_bf16_f32 v33, v37, v33
	v_cvt_pk_bf16_f32 v34, v38, v34
	v_cvt_pk_bf16_f32 v35, v39, v35
	global_store_dwordx4 v[116:117], v[32:35], off
	v_fmamk_f32 v101, v101, 0x3b000000, v190
	v_mul_f32_e32 v132, 0x4f800000, v101
	v_cmp_gt_f32_e32 vcc, s73, v101
	s_nop 1
	v_cndmask_b32_e32 v101, v101, v132, vcc
	v_sqrt_f32_e32 v132, v101
	s_nop 0
	v_add_u32_e32 v133, -1, v132
	v_add_u32_e32 v134, 1, v132
	v_fma_f32 v135, -v133, v132, v101
	v_fma_f32 v136, -v134, v132, v101
	v_cmp_ge_f32_e64 s[40:41], 0, v135
	s_nop 1
	v_cndmask_b32_e64 v132, v132, v133, s[40:41]
	v_cmp_lt_f32_e64 s[40:41], 0, v136
	s_nop 1
	v_cndmask_b32_e64 v132, v132, v134, s[40:41]
	v_mul_f32_e32 v133, 0x37800000, v132
	v_cndmask_b32_e32 v132, v132, v133, vcc
	v_cmp_class_f32_e32 vcc, v101, v191
	s_nop 1
	v_cndmask_b32_e32 v101, v132, v101, vcc
	v_div_scale_f32 v132, s[14:15], v101, v101, 1.0
	v_rcp_f32_e32 v133, v132
	v_div_scale_f32 v134, vcc, 1.0, v101, 1.0
	v_fma_f32 v135, -v132, v133, 1.0
	v_fmac_f32_e32 v133, v135, v133
	v_mul_f32_e32 v135, v134, v133
	v_fma_f32 v136, -v132, v135, v134
	v_fmac_f32_e32 v135, v136, v133
	v_fma_f32 v132, -v132, v135, v134
	v_div_fmas_f32 v132, v132, v133, v135
	v_div_fixup_f32 v101, v132, v101, 1.0
	v_mul_f32_e32 v44, v101, v44
	v_mul_f32_e32 v40, v101, v40
	v_mul_f32_e32 v45, v101, v45
	v_mul_f32_e32 v41, v101, v41
	v_mul_f32_e32 v46, v101, v46
; __device__ __forceinline__ unsigned pk2(float lo, float hi) { unsigned r; asm volatile("v_cvt_pk_bf16_f32 %0, %1, %2" : "=v"(r) : "v"(lo), "v"(hi)); return r; }
; __device__ __forceinline__ void rms512_inplace(bf16* __restrict__ A, int gw, int NGW, int lane) {
;     ...
;         const float rstd = 1.f / sqrtf(wave_sum(s) * (1.f / 512) + EPS_);
;         v4u o; o.x = pk2(f[0] * rstd, f[1] * rstd); o.y = pk2(f[2] * rstd, f[3] * rstd); o.z = pk2(f[4] * rstd, f[5] * rstd); o.w = pk2(f[6] * rstd, f[7] * rstd); *p = o;
	v_mul_f32_e32 v42, v101, v42
	v_mul_f32_e32 v47, v101, v47
	v_mul_f32_e32 v43, v101, v43
	v_cvt_pk_bf16_f32 v40, v44, v40
	v_cvt_pk_bf16_f32 v41, v45, v41
	v_cvt_pk_bf16_f32 v42, v46, v42
	v_cvt_pk_bf16_f32 v43, v47, v43
	global_store_dwordx4 v[118:119], v[40:43], off
	v_fmamk_f32 v102, v102, 0x3b000000, v190
	v_mul_f32_e32 v132, 0x4f800000, v102
	v_cmp_gt_f32_e32 vcc, s73, v102
	s_nop 1
	v_cndmask_b32_e32 v102, v102, v132, vcc
	v_sqrt_f32_e32 v132, v102
	s_nop 0
	v_add_u32_e32 v133, -1, v132
	v_add_u32_e32 v134, 1, v132
	v_fma_f32 v135, -v133, v132, v102
	v_fma_f32 v136, -v134, v132, v102
	v_cmp_ge_f32_e64 s[40:41], 0, v135
	s_nop 1
	v_cndmask_b32_e64 v132, v132, v133, s[40:41]
	v_cmp_lt_f32_e64 s[40:41], 0, v136
	s_nop 1
	v_cndmask_b32_e64 v132, v132, v134, s[40:41]
	v_mul_f32_e32 v133, 0x37800000, v132
	v_cndmask_b32_e32 v132, v132, v133, vcc
	v_cmp_class_f32_e32 vcc, v102, v191
	s_nop 1
	v_cndmask_b32_e32 v102, v132, v102, vcc
	v_div_scale_f32 v132, s[14:15], v102, v102, 1.0
	v_rcp_f32_e32 v133, v132
	v_div_scale_f32 v134, vcc, 1.0, v102, 1.0
	v_fma_f32 v135, -v132, v133, 1.0
	v_fmac_f32_e32 v133, v135, v133
	v_mul_f32_e32 v135, v134, v133
	v_fma_f32 v136, -v132, v135, v134
	v_fmac_f32_e32 v135, v136, v133
	v_fma_f32 v132, -v132, v135, v134
	v_div_fmas_f32 v132, v132, v133, v135
	v_div_fixup_f32 v102, v132, v102, 1.0
	v_mul_f32_e32 v52, v102, v52
	v_mul_f32_e32 v48, v102, v48
	v_mul_f32_e32 v53, v102, v53
	v_mul_f32_e32 v49, v102, v49
	v_mul_f32_e32 v54, v102, v54
	v_mul_f32_e32 v50, v102, v50
	v_mul_f32_e32 v55, v102, v55
	v_mul_f32_e32 v51, v102, v51
	v_cvt_pk_bf16_f32 v48, v52, v48
	v_cvt_pk_bf16_f32 v49, v53, v49
	v_cvt_pk_bf16_f32 v50, v54, v50
	v_cvt_pk_bf16_f32 v51, v55, v51
	global_store_dwordx4 v[120:121], v[48:51], off
	v_fmamk_f32 v103, v103, 0x3b000000, v190
	v_mul_f32_e32 v132, 0x4f800000, v103
	v_cmp_gt_f32_e32 vcc, s73, v103
	s_nop 1
	v_cndmask_b32_e32 v103, v103, v132, vcc
	v_sqrt_f32_e32 v132, v103
	s_nop 0
	v_add_u32_e32 v133, -1, v132
	v_add_u32_e32 v134, 1, v132
	v_fma_f32 v135, -v133, v132, v103
	v_fma_f32 v136, -v134, v132, v103
	v_cmp_ge_f32_e64 s[40:41], 0, v135
	s_nop 1
	v_cndmask_b32_e64 v132, v132, v133, s[40:41]
	v_cmp_lt_f32_e64 s[40:41], 0, v136
	s_nop 1
	v_cndmask_b32_e64 v132, v132, v134, s[40:41]
	v_mul_f32_e32 v133, 0x37800000, v132
	v_cndmask_b32_e32 v132, v132, v133, vcc
	v_cmp_class_f32_e32 vcc, v103, v191
	s_nop 1
	v_cndmask_b32_e32 v103, v132, v103, vcc
	v_div_scale_f32 v132, s[14:15], v103, v103, 1.0
	v_rcp_f32_e32 v133, v132
	v_div_scale_f32 v134, vcc, 1.0, v103, 1.0
	v_fma_f32 v135, -v132, v133, 1.0
	v_fmac_f32_e32 v133, v135, v133
	v_mul_f32_e32 v135, v134, v133
	v_fma_f32 v136, -v132, v135, v134
	v_fmac_f32_e32 v135, v136, v133
	v_fma_f32 v132, -v132, v135, v134
	v_div_fmas_f32 v132, v132, v133, v135
	v_div_fixup_f32 v103, v132, v103, 1.0
	v_mul_f32_e32 v60, v103, v60
	v_mul_f32_e32 v56, v103, v56
	v_mul_f32_e32 v61, v103, v61
	v_mul_f32_e32 v57, v103, v57
	v_mul_f32_e32 v62, v103, v62
	v_mul_f32_e32 v58, v103, v58
	v_mul_f32_e32 v63, v103, v63
	v_mul_f32_e32 v59, v103, v59
	v_cvt_pk_bf16_f32 v56, v60, v56
	v_cvt_pk_bf16_f32 v57, v61, v57
	v_cvt_pk_bf16_f32 v58, v62, v58
	v_cvt_pk_bf16_f32 v59, v63, v59
	global_store_dwordx4 v[122:123], v[56:59], off
	v_fmamk_f32 v104, v104, 0x3b000000, v190
	v_mul_f32_e32 v132, 0x4f800000, v104
	v_cmp_gt_f32_e32 vcc, s73, v104
	s_nop 1
	v_cndmask_b32_e32 v104, v104, v132, vcc
	v_sqrt_f32_e32 v132, v104
	s_nop 0
	v_add_u32_e32 v133, -1, v132
	v_add_u32_e32 v134, 1, v132
	v_fma_f32 v135, -v133, v132, v104
	v_fma_f32 v136, -v134, v132, v104
	v_cmp_ge_f32_e64 s[40:41], 0, v135
	s_nop 1
	v_cndmask_b32_e64 v132, v132, v133, s[40:41]
	v_cmp_lt_f32_e64 s[40:41], 0, v136
	s_nop 1
	v_cndmask_b32_e64 v132, v132, v134, s[40:41]
	v_mul_f32_e32 v133, 0x37800000, v132
	v_cndmask_b32_e32 v132, v132, v133, vcc
	v_cmp_class_f32_e32 vcc, v104, v191
	s_nop 1
	v_cndmask_b32_e32 v104, v132, v104, vcc
	v_div_scale_f32 v132, s[14:15], v104, v104, 1.0
	v_rcp_f32_e32 v133, v132
	v_div_scale_f32 v134, vcc, 1.0, v104, 1.0
	v_fma_f32 v135, -v132, v133, 1.0
	v_fmac_f32_e32 v133, v135, v133
	v_mul_f32_e32 v135, v134, v133
	v_fma_f32 v136, -v132, v135, v134
	v_fmac_f32_e32 v135, v136, v133
	v_fma_f32 v132, -v132, v135, v134
	v_div_fmas_f32 v132, v132, v133, v135
	v_div_fixup_f32 v104, v132, v104, 1.0
	v_mul_f32_e32 v68, v104, v68
	v_mul_f32_e32 v64, v104, v64
	v_mul_f32_e32 v69, v104, v69
	v_mul_f32_e32 v65, v104, v65
	v_mul_f32_e32 v70, v104, v70
	v_mul_f32_e32 v66, v104, v66
	v_mul_f32_e32 v71, v104, v71
	v_mul_f32_e32 v67, v104, v67
	v_cvt_pk_bf16_f32 v64, v68, v64
	v_cvt_pk_bf16_f32 v65, v69, v65
	v_cvt_pk_bf16_f32 v66, v70, v66
	v_cvt_pk_bf16_f32 v67, v71, v67
; __device__ __forceinline__ unsigned pk2(float lo, float hi) { unsigned r; asm volatile("v_cvt_pk_bf16_f32 %0, %1, %2" : "=v"(r) : "v"(lo), "v"(hi)); return r; }
; __device__ __forceinline__ float bflo(unsigned w) { return __uint_as_float(w << 16); }
; __device__ __forceinline__ float bfhi(unsigned w) { return __uint_as_float(w & 0xffff0000u); }
; __device__ __forceinline__ void rms512_inplace(bf16* __restrict__ A, int gw, int NGW, int lane) {
;     for (int m = gw; m < S_; m += NGW) {
;         v4u* p = (v4u*)(A + (size_t)m * 512) + lane; const v4u w = *p;
;         float f[8] = {bflo(w.x), bfhi(w.x), bflo(w.y), bfhi(w.y), bflo(w.z), bfhi(w.z), bflo(w.w), bfhi(w.w)}; float s = 0.f;
; #pragma unroll
;         for (int e = 0; e < 8; ++e) s += f[e] * f[e];
;         const float rstd = 1.f / sqrtf(wave_sum(s) * (1.f / 512) + EPS_);
;         v4u o; o.x = pk2(f[0] * rstd, f[1] * rstd); o.y = pk2(f[2] * rstd, f[3] * rstd); o.z = pk2(f[4] * rstd, f[5] * rstd); o.w = pk2(f[6] * rstd, f[7] * rstd); *p = o;
;     }
	global_store_dwordx4 v[124:125], v[64:67], off
	v_fmamk_f32 v105, v105, 0x3b000000, v190
	v_mul_f32_e32 v132, 0x4f800000, v105
	v_cmp_gt_f32_e32 vcc, s73, v105
	s_nop 1
	v_cndmask_b32_e32 v105, v105, v132, vcc
	v_sqrt_f32_e32 v132, v105
	s_nop 0
	v_add_u32_e32 v133, -1, v132
	v_add_u32_e32 v134, 1, v132
	v_fma_f32 v135, -v133, v132, v105
	v_fma_f32 v136, -v134, v132, v105
	v_cmp_ge_f32_e64 s[40:41], 0, v135
	s_nop 1
	v_cndmask_b32_e64 v132, v132, v133, s[40:41]
	v_cmp_lt_f32_e64 s[40:41], 0, v136
	s_nop 1
	v_cndmask_b32_e64 v132, v132, v134, s[40:41]
	v_mul_f32_e32 v133, 0x37800000, v132
	v_cndmask_b32_e32 v132, v132, v133, vcc
	v_cmp_class_f32_e32 vcc, v105, v191
	s_nop 1
	v_cndmask_b32_e32 v105, v132, v105, vcc
	v_div_scale_f32 v132, s[14:15], v105, v105, 1.0
	v_rcp_f32_e32 v133, v132
	v_div_scale_f32 v134, vcc, 1.0, v105, 1.0
	v_fma_f32 v135, -v132, v133, 1.0
	v_fmac_f32_e32 v133, v135, v133
	v_mul_f32_e32 v135, v134, v133
	v_fma_f32 v136, -v132, v135, v134
	v_fmac_f32_e32 v135, v136, v133
	v_fma_f32 v132, -v132, v135, v134
	v_div_fmas_f32 v132, v132, v133, v135
	v_div_fixup_f32 v105, v132, v105, 1.0
	v_mul_f32_e32 v76, v105, v76
	v_mul_f32_e32 v72, v105, v72
	v_mul_f32_e32 v77, v105, v77
	v_mul_f32_e32 v73, v105, v73
	v_mul_f32_e32 v78, v105, v78
	v_mul_f32_e32 v74, v105, v74
	v_mul_f32_e32 v79, v105, v79
	v_mul_f32_e32 v75, v105, v75
	v_cvt_pk_bf16_f32 v72, v76, v72
	v_cvt_pk_bf16_f32 v73, v77, v73
	v_cvt_pk_bf16_f32 v74, v78, v74
	v_cvt_pk_bf16_f32 v75, v79, v75
	global_store_dwordx4 v[126:127], v[72:75], off
	v_fmamk_f32 v106, v106, 0x3b000000, v190
	v_mul_f32_e32 v132, 0x4f800000, v106
	v_cmp_gt_f32_e32 vcc, s73, v106
	s_nop 1
	v_cndmask_b32_e32 v106, v106, v132, vcc
	v_sqrt_f32_e32 v132, v106
	s_nop 0
	v_add_u32_e32 v133, -1, v132
	v_add_u32_e32 v134, 1, v132
	v_fma_f32 v135, -v133, v132, v106
	v_fma_f32 v136, -v134, v132, v106
	v_cmp_ge_f32_e64 s[40:41], 0, v135
	s_nop 1
	v_cndmask_b32_e64 v132, v132, v133, s[40:41]
	v_cmp_lt_f32_e64 s[40:41], 0, v136
	s_nop 1
	v_cndmask_b32_e64 v132, v132, v134, s[40:41]
	v_mul_f32_e32 v133, 0x37800000, v132
	v_cndmask_b32_e32 v132, v132, v133, vcc
	v_cmp_class_f32_e32 vcc, v106, v191
	s_nop 1
	v_cndmask_b32_e32 v106, v132, v106, vcc
	v_div_scale_f32 v132, s[14:15], v106, v106, 1.0
	v_rcp_f32_e32 v133, v132
	v_div_scale_f32 v134, vcc, 1.0, v106, 1.0
	v_fma_f32 v135, -v132, v133, 1.0
	v_fmac_f32_e32 v133, v135, v133
	v_mul_f32_e32 v135, v134, v133
	v_fma_f32 v136, -v132, v135, v134
	v_fmac_f32_e32 v135, v136, v133
	v_fma_f32 v132, -v132, v135, v134
	v_div_fmas_f32 v132, v132, v133, v135
	v_div_fixup_f32 v106, v132, v106, 1.0
	v_mul_f32_e32 v84, v106, v84
	v_mul_f32_e32 v80, v106, v80
	v_mul_f32_e32 v85, v106, v85
	v_mul_f32_e32 v81, v106, v81
	v_mul_f32_e32 v86, v106, v86
	v_mul_f32_e32 v82, v106, v82
	v_mul_f32_e32 v87, v106, v87
	v_mul_f32_e32 v83, v106, v83
	v_cvt_pk_bf16_f32 v80, v84, v80
	v_cvt_pk_bf16_f32 v81, v85, v81
	v_cvt_pk_bf16_f32 v82, v86, v82
	v_cvt_pk_bf16_f32 v83, v87, v83
	global_store_dwordx4 v[128:129], v[80:83], off
	v_fmamk_f32 v107, v107, 0x3b000000, v190
	v_mul_f32_e32 v132, 0x4f800000, v107
	v_cmp_gt_f32_e32 vcc, s73, v107
	s_nop 1
	v_cndmask_b32_e32 v107, v107, v132, vcc
	v_sqrt_f32_e32 v132, v107
	s_nop 0
	v_add_u32_e32 v133, -1, v132
	v_add_u32_e32 v134, 1, v132
	v_fma_f32 v135, -v133, v132, v107
	v_fma_f32 v136, -v134, v132, v107
	v_cmp_ge_f32_e64 s[40:41], 0, v135
	s_nop 1
	v_cndmask_b32_e64 v132, v132, v133, s[40:41]
	v_cmp_lt_f32_e64 s[40:41], 0, v136
	s_nop 1
	v_cndmask_b32_e64 v132, v132, v134, s[40:41]
	v_mul_f32_e32 v133, 0x37800000, v132
	v_cndmask_b32_e32 v132, v132, v133, vcc
	v_cmp_class_f32_e32 vcc, v107, v191
	s_nop 1
	v_cndmask_b32_e32 v107, v132, v107, vcc
	v_div_scale_f32 v132, s[14:15], v107, v107, 1.0
	v_rcp_f32_e32 v133, v132
	v_div_scale_f32 v134, vcc, 1.0, v107, 1.0
	v_fma_f32 v135, -v132, v133, 1.0
	v_fmac_f32_e32 v133, v135, v133
	v_mul_f32_e32 v135, v134, v133
	v_fma_f32 v136, -v132, v135, v134
	v_fmac_f32_e32 v135, v136, v133
	v_fma_f32 v132, -v132, v135, v134
	v_div_fmas_f32 v132, v132, v133, v135
	v_div_fixup_f32 v107, v132, v107, 1.0
	v_mul_f32_e32 v92, v107, v92
	v_mul_f32_e32 v88, v107, v88
	v_mul_f32_e32 v93, v107, v93
	v_mul_f32_e32 v89, v107, v89
	v_mul_f32_e32 v94, v107, v94
	v_mul_f32_e32 v90, v107, v90
	v_mul_f32_e32 v95, v107, v95
	v_mul_f32_e32 v91, v107, v91
	v_cvt_pk_bf16_f32 v88, v92, v88
	v_cvt_pk_bf16_f32 v89, v93, v89
	v_cvt_pk_bf16_f32 v90, v94, v90
	v_cvt_pk_bf16_f32 v91, v95, v91
	global_store_dwordx4 v[130:131], v[88:91], off
	v_lshl_add_u64 v[4:5], v[130:131], 0, s[12:13]
	s_lshl_b32 s14, s10, 3
	s_add_i32 s11, s11, s14
	s_cmpk_lt_i32 s11, 0x4000
	s_cbranch_scc1 .Lrms_q_batch
	s_branch .Lrms_q_done

; __device__ __forceinline__ float bflo(unsigned w) { return __uint_as_float(w << 16); }
; __device__ __forceinline__ float bfhi(unsigned w) { return __uint_as_float(w & 0xffff0000u); }
; __device__ __forceinline__ void rms512_inplace(bf16* __restrict__ A, int gw, int NGW, int lane) {
;     for (int m = gw; m < S_; m += NGW) {
;         v4u* p = (v4u*)(A + (size_t)m * 512) + lane; const v4u w = *p;
;         float f[8] = {bflo(w.x), bfhi(w.x), bflo(w.y), bfhi(w.y), bflo(w.z), bfhi(w.z), bflo(w.w), bfhi(w.w)}; float s = 0.f;
; #pragma unroll
;         for (int e = 0; e < 8; ++e) s += f[e] * f[e];
; __global__ void __launch_bounds__(NWAVES * 64, 2) mega_fwd(Args args) {
;     ...
;             rms512_inplace(WB(WS_QL), gw, NGW, lane); rms512_inplace(WB(WS_KVL), gw, NGW, lane);
.Lrms_q_done:
	s_mov_b64 s[14:15], 0x1a200000
	v_lshl_add_u64 v[2:3], v[2:3], 0, s[14:15]
.Lrms_kv_batch:
	s_mul_i32 s14, s10, 7
	s_add_i32 s14, s14, s5
	s_cmpk_lt_i32 s14, 0x4000
	s_cbranch_scc0 .LBB0_1063
	v_mov_b32_e32 v116, v2
	v_mov_b32_e32 v117, v3
	v_lshl_add_u64 v[118:119], v[116:117], 0, s[12:13]
	v_lshl_add_u64 v[120:121], v[118:119], 0, s[12:13]
	v_lshl_add_u64 v[122:123], v[120:121], 0, s[12:13]
	v_lshl_add_u64 v[124:125], v[122:123], 0, s[12:13]
	v_lshl_add_u64 v[126:127], v[124:125], 0, s[12:13]
	v_lshl_add_u64 v[128:129], v[126:127], 0, s[12:13]
	v_lshl_add_u64 v[130:131], v[128:129], 0, s[12:13]
	global_load_dwordx4 v[32:35], v[116:117], off
	global_load_dwordx4 v[40:43], v[118:119], off
	global_load_dwordx4 v[48:51], v[120:121], off
	global_load_dwordx4 v[56:59], v[122:123], off
	global_load_dwordx4 v[64:67], v[124:125], off
	global_load_dwordx4 v[72:75], v[126:127], off
	global_load_dwordx4 v[80:83], v[128:129], off
	global_load_dwordx4 v[88:91], v[130:131], off
	s_waitcnt vmcnt(7)
	v_lshlrev_b32_e32 v36, 16, v32
	v_and_b32_e32 v32, 0xffff0000, v32
	v_mul_f32_e32 v100, v32, v32
	v_lshlrev_b32_e32 v37, 16, v33
	v_fmac_f32_e32 v100, v36, v36
	v_and_b32_e32 v33, 0xffff0000, v33
	v_fmac_f32_e32 v100, v37, v37
	v_lshlrev_b32_e32 v38, 16, v34
	v_fmac_f32_e32 v100, v33, v33
	v_and_b32_e32 v34, 0xffff0000, v34
	v_fmac_f32_e32 v100, v38, v38
	v_lshlrev_b32_e32 v39, 16, v35
	v_fmac_f32_e32 v100, v34, v34
	v_and_b32_e32 v35, 0xffff0000, v35
	v_fmac_f32_e32 v100, v39, v39
	v_fmac_f32_e32 v100, v35, v35
	s_waitcnt vmcnt(6)
	v_lshlrev_b32_e32 v44, 16, v40
	v_and_b32_e32 v40, 0xffff0000, v40
	v_mul_f32_e32 v101, v40, v40
	v_lshlrev_b32_e32 v45, 16, v41
	v_fmac_f32_e32 v101, v44, v44
	v_and_b32_e32 v41, 0xffff0000, v41
	v_fmac_f32_e32 v101, v45, v45
	v_lshlrev_b32_e32 v46, 16, v42
	v_fmac_f32_e32 v101, v41, v41
	v_and_b32_e32 v42, 0xffff0000, v42
	v_fmac_f32_e32 v101, v46, v46
	v_lshlrev_b32_e32 v47, 16, v43
	v_fmac_f32_e32 v101, v42, v42
	v_and_b32_e32 v43, 0xffff0000, v43
	v_fmac_f32_e32 v101, v47, v47
	v_fmac_f32_e32 v101, v43, v43
	s_waitcnt vmcnt(5)
	v_lshlrev_b32_e32 v52, 16, v48
	v_and_b32_e32 v48, 0xffff0000, v48
	v_mul_f32_e32 v102, v48, v48
	v_lshlrev_b32_e32 v53, 16, v49
	v_fmac_f32_e32 v102, v52, v52
	v_and_b32_e32 v49, 0xffff0000, v49
	v_fmac_f32_e32 v102, v53, v53
	v_lshlrev_b32_e32 v54, 16, v50
	v_fmac_f32_e32 v102, v49, v49
	v_and_b32_e32 v50, 0xffff0000, v50
	v_fmac_f32_e32 v102, v54, v54
	v_lshlrev_b32_e32 v55, 16, v51
	v_fmac_f32_e32 v102, v50, v50
	v_and_b32_e32 v51, 0xffff0000, v51
	v_fmac_f32_e32 v102, v55, v55
	v_fmac_f32_e32 v102, v51, v51
	s_waitcnt vmcnt(4)
	v_lshlrev_b32_e32 v60, 16, v56
	v_and_b32_e32 v56, 0xffff0000, v56
	v_mul_f32_e32 v103, v56, v56
	v_lshlrev_b32_e32 v61, 16, v57
	v_fmac_f32_e32 v103, v60, v60
	v_and_b32_e32 v57, 0xffff0000, v57
	v_fmac_f32_e32 v103, v61, v61
	v_lshlrev_b32_e32 v62, 16, v58
	v_fmac_f32_e32 v103, v57, v57
	v_and_b32_e32 v58, 0xffff0000, v58
	v_fmac_f32_e32 v103, v62, v62
	v_lshlrev_b32_e32 v63, 16, v59
	v_fmac_f32_e32 v103, v58, v58
	v_and_b32_e32 v59, 0xffff0000, v59
	v_fmac_f32_e32 v103, v63, v63
	v_fmac_f32_e32 v103, v59, v59
	s_waitcnt vmcnt(3)
	v_lshlrev_b32_e32 v68, 16, v64
	v_and_b32_e32 v64, 0xffff0000, v64
	v_mul_f32_e32 v104, v64, v64
	v_lshlrev_b32_e32 v69, 16, v65
	v_fmac_f32_e32 v104, v68, v68
	v_and_b32_e32 v65, 0xffff0000, v65
	v_fmac_f32_e32 v104, v69, v69
	v_lshlrev_b32_e32 v70, 16, v66
	v_fmac_f32_e32 v104, v65, v65
	v_and_b32_e32 v66, 0xffff0000, v66
	v_fmac_f32_e32 v104, v70, v70
	v_lshlrev_b32_e32 v71, 16, v67
	v_fmac_f32_e32 v104, v66, v66
	v_and_b32_e32 v67, 0xffff0000, v67
	v_fmac_f32_e32 v104, v71, v71
	v_fmac_f32_e32 v104, v67, v67
	s_waitcnt vmcnt(2)
	v_lshlrev_b32_e32 v76, 16, v72
	v_and_b32_e32 v72, 0xffff0000, v72
	v_mul_f32_e32 v105, v72, v72
	v_lshlrev_b32_e32 v77, 16, v73
	v_fmac_f32_e32 v105, v76, v76
	v_and_b32_e32 v73, 0xffff0000, v73
	v_fmac_f32_e32 v105, v77, v77
	v_lshlrev_b32_e32 v78, 16, v74
	v_fmac_f32_e32 v105, v73, v73
	v_and_b32_e32 v74, 0xffff0000, v74
	v_fmac_f32_e32 v105, v78, v78
	v_lshlrev_b32_e32 v79, 16, v75
	v_fmac_f32_e32 v105, v74, v74
	v_and_b32_e32 v75, 0xffff0000, v75
	v_fmac_f32_e32 v105, v79, v79
	v_fmac_f32_e32 v105, v75, v75
	s_waitcnt vmcnt(1)
	v_lshlrev_b32_e32 v84, 16, v80
	v_and_b32_e32 v80, 0xffff0000, v80
	v_mul_f32_e32 v106, v80, v80
	v_lshlrev_b32_e32 v85, 16, v81
	v_fmac_f32_e32 v106, v84, v84
	v_and_b32_e32 v81, 0xffff0000, v81
	v_fmac_f32_e32 v106, v85, v85
	v_lshlrev_b32_e32 v86, 16, v82
	v_fmac_f32_e32 v106, v81, v81
	v_and_b32_e32 v82, 0xffff0000, v82
	v_fmac_f32_e32 v106, v86, v86
	v_lshlrev_b32_e32 v87, 16, v83
	v_fmac_f32_e32 v106, v82, v82
	v_and_b32_e32 v83, 0xffff0000, v83
	v_fmac_f32_e32 v106, v87, v87
	v_fmac_f32_e32 v106, v83, v83
	s_waitcnt vmcnt(0)
	v_lshlrev_b32_e32 v92, 16, v88
	v_and_b32_e32 v88, 0xffff0000, v88
	v_mul_f32_e32 v107, v88, v88
	v_lshlrev_b32_e32 v93, 16, v89
	v_fmac_f32_e32 v107, v92, v92
	v_and_b32_e32 v89, 0xffff0000, v89
	v_fmac_f32_e32 v107, v93, v93
	v_lshlrev_b32_e32 v94, 16, v90
	v_fmac_f32_e32 v107, v89, v89
	v_and_b32_e32 v90, 0xffff0000, v90
	v_fmac_f32_e32 v107, v94, v94
	v_lshlrev_b32_e32 v95, 16, v91
	v_fmac_f32_e32 v107, v90, v90
	v_and_b32_e32 v91, 0xffff0000, v91
	v_fmac_f32_e32 v107, v95, v95
	v_fmac_f32_e32 v107, v91, v91
	ds_bpermute_b32 v108, v0, v100
	ds_bpermute_b32 v109, v0, v101
	ds_bpermute_b32 v110, v0, v102
	ds_bpermute_b32 v111, v0, v103
	ds_bpermute_b32 v112, v0, v104
	ds_bpermute_b32 v113, v0, v105
	ds_bpermute_b32 v114, v0, v106
	ds_bpermute_b32 v115, v0, v107
	s_waitcnt lgkmcnt(0)
; __device__ __forceinline__ unsigned pk2(float lo, float hi) { unsigned r; asm volatile("v_cvt_pk_bf16_f32 %0, %1, %2" : "=v"(r) : "v"(lo), "v"(hi)); return r; }
; __device__ __forceinline__ float wave_sum(float v) {
; #pragma unroll
;     for (int o = 1; o < 64; o <<= 1) v += __shfl_xor(v, o);
;     return v;
; }
; __device__ __forceinline__ void rms512_inplace(bf16* __restrict__ A, int gw, int NGW, int lane) {
;     ...
;         const float rstd = 1.f / sqrtf(wave_sum(s) * (1.f / 512) + EPS_);
;         v4u o; o.x = pk2(f[0] * rstd, f[1] * rstd); o.y = pk2(f[2] * rstd, f[3] * rstd); o.z = pk2(f[4] * rstd, f[5] * rstd); o.w = pk2(f[6] * rstd, f[7] * rstd); *p = o;
	v_add_f32_e32 v100, v100, v108
	v_add_f32_e32 v101, v101, v109
	v_add_f32_e32 v102, v102, v110
	v_add_f32_e32 v103, v103, v111
	v_add_f32_e32 v104, v104, v112
	v_add_f32_e32 v105, v105, v113
	v_add_f32_e32 v106, v106, v114
	v_add_f32_e32 v107, v107, v115
	ds_bpermute_b32 v108, v6, v100
	ds_bpermute_b32 v109, v6, v101
	ds_bpermute_b32 v110, v6, v102
	ds_bpermute_b32 v111, v6, v103
	ds_bpermute_b32 v112, v6, v104
	ds_bpermute_b32 v113, v6, v105
	ds_bpermute_b32 v114, v6, v106
	ds_bpermute_b32 v115, v6, v107
	s_waitcnt lgkmcnt(0)
	v_add_f32_e32 v100, v100, v108
	v_add_f32_e32 v101, v101, v109
	v_add_f32_e32 v102, v102, v110
	v_add_f32_e32 v103, v103, v111
	v_add_f32_e32 v104, v104, v112
	v_add_f32_e32 v105, v105, v113
	v_add_f32_e32 v106, v106, v114
	v_add_f32_e32 v107, v107, v115
	ds_bpermute_b32 v108, v7, v100
	ds_bpermute_b32 v109, v7, v101
	ds_bpermute_b32 v110, v7, v102
	ds_bpermute_b32 v111, v7, v103
	ds_bpermute_b32 v112, v7, v104
	ds_bpermute_b32 v113, v7, v105
	ds_bpermute_b32 v114, v7, v106
	ds_bpermute_b32 v115, v7, v107
	s_waitcnt lgkmcnt(0)
	v_add_f32_e32 v100, v100, v108
	v_add_f32_e32 v101, v101, v109
	v_add_f32_e32 v102, v102, v110
	v_add_f32_e32 v103, v103, v111
	v_add_f32_e32 v104, v104, v112
	v_add_f32_e32 v105, v105, v113
	v_add_f32_e32 v106, v106, v114
	v_add_f32_e32 v107, v107, v115
	ds_bpermute_b32 v108, v8, v100
	ds_bpermute_b32 v109, v8, v101
	ds_bpermute_b32 v110, v8, v102
	ds_bpermute_b32 v111, v8, v103
	ds_bpermute_b32 v112, v8, v104
	ds_bpermute_b32 v113, v8, v105
	ds_bpermute_b32 v114, v8, v106
	ds_bpermute_b32 v115, v8, v107
	s_waitcnt lgkmcnt(0)
	v_add_f32_e32 v100, v100, v108
	v_add_f32_e32 v101, v101, v109
	v_add_f32_e32 v102, v102, v110
	v_add_f32_e32 v103, v103, v111
	v_add_f32_e32 v104, v104, v112
	v_add_f32_e32 v105, v105, v113
	v_add_f32_e32 v106, v106, v114
	v_add_f32_e32 v107, v107, v115
	ds_bpermute_b32 v108, v9, v100
	ds_bpermute_b32 v109, v9, v101
	ds_bpermute_b32 v110, v9, v102
	ds_bpermute_b32 v111, v9, v103
	ds_bpermute_b32 v112, v9, v104
	ds_bpermute_b32 v113, v9, v105
	ds_bpermute_b32 v114, v9, v106
	ds_bpermute_b32 v115, v9, v107
	s_waitcnt lgkmcnt(0)
	v_add_f32_e32 v100, v100, v108
	v_add_f32_e32 v101, v101, v109
	v_add_f32_e32 v102, v102, v110
	v_add_f32_e32 v103, v103, v111
	v_add_f32_e32 v104, v104, v112
	v_add_f32_e32 v105, v105, v113
	v_add_f32_e32 v106, v106, v114
	v_add_f32_e32 v107, v107, v115
	ds_bpermute_b32 v108, v10, v100
	ds_bpermute_b32 v109, v10, v101
	ds_bpermute_b32 v110, v10, v102
	ds_bpermute_b32 v111, v10, v103
	ds_bpermute_b32 v112, v10, v104
	ds_bpermute_b32 v113, v10, v105
	ds_bpermute_b32 v114, v10, v106
	ds_bpermute_b32 v115, v10, v107
	s_waitcnt lgkmcnt(0)
	v_add_f32_e32 v100, v100, v108
	v_add_f32_e32 v101, v101, v109
	v_add_f32_e32 v102, v102, v110
	v_add_f32_e32 v103, v103, v111
	v_add_f32_e32 v104, v104, v112
	v_add_f32_e32 v105, v105, v113
	v_add_f32_e32 v106, v106, v114
	v_add_f32_e32 v107, v107, v115
	v_fmamk_f32 v100, v100, 0x3b000000, v190
	v_mul_f32_e32 v132, 0x4f800000, v100
	v_cmp_gt_f32_e32 vcc, s73, v100
	s_nop 1
	v_cndmask_b32_e32 v100, v100, v132, vcc
	v_sqrt_f32_e32 v132, v100
	s_nop 0
	v_add_u32_e32 v133, -1, v132
	v_add_u32_e32 v134, 1, v132
	v_fma_f32 v135, -v133, v132, v100
	v_fma_f32 v136, -v134, v132, v100
	v_cmp_ge_f32_e64 s[40:41], 0, v135
	s_nop 1
	v_cndmask_b32_e64 v132, v132, v133, s[40:41]
	v_cmp_lt_f32_e64 s[40:41], 0, v136
	s_nop 1
	v_cndmask_b32_e64 v132, v132, v134, s[40:41]
	v_mul_f32_e32 v133, 0x37800000, v132
	v_cndmask_b32_e32 v132, v132, v133, vcc
	v_cmp_class_f32_e32 vcc, v100, v191
	s_nop 1
	v_cndmask_b32_e32 v100, v132, v100, vcc
	v_div_scale_f32 v132, s[14:15], v100, v100, 1.0
	v_rcp_f32_e32 v133, v132
	v_div_scale_f32 v134, vcc, 1.0, v100, 1.0
	v_fma_f32 v135, -v132, v133, 1.0
	v_fmac_f32_e32 v133, v135, v133
	v_mul_f32_e32 v135, v134, v133
	v_fma_f32 v136, -v132, v135, v134
	v_fmac_f32_e32 v135, v136, v133
	v_fma_f32 v132, -v132, v135, v134
	v_div_fmas_f32 v132, v132, v133, v135
	v_div_fixup_f32 v100, v132, v100, 1.0
	v_mul_f32_e32 v36, v100, v36
	v_mul_f32_e32 v32, v100, v32
	v_mul_f32_e32 v37, v100, v37
	v_mul_f32_e32 v33, v100, v33
	v_mul_f32_e32 v38, v100, v38
	v_mul_f32_e32 v34, v100, v34
	v_mul_f32_e32 v39, v100, v39
	v_mul_f32_e32 v35, v100, v35
	v_cvt_pk_bf16_f32 v32, v36, v32
	v_cvt_pk_bf16_f32 v33, v37, v33
	v_cvt_pk_bf16_f32 v34, v38, v34
	v_cvt_pk_bf16_f32 v35, v39, v35
	global_store_dwordx4 v[116:117], v[32:35], off
	v_fmamk_f32 v101, v101, 0x3b000000, v190
	v_mul_f32_e32 v132, 0x4f800000, v101
	v_cmp_gt_f32_e32 vcc, s73, v101
	s_nop 1
	v_cndmask_b32_e32 v101, v101, v132, vcc
	v_sqrt_f32_e32 v132, v101
	s_nop 0
	v_add_u32_e32 v133, -1, v132
	v_add_u32_e32 v134, 1, v132
	v_fma_f32 v135, -v133, v132, v101
	v_fma_f32 v136, -v134, v132, v101
	v_cmp_ge_f32_e64 s[40:41], 0, v135
	s_nop 1
	v_cndmask_b32_e64 v132, v132, v133, s[40:41]
	v_cmp_lt_f32_e64 s[40:41], 0, v136
	s_nop 1
	v_cndmask_b32_e64 v132, v132, v134, s[40:41]
	v_mul_f32_e32 v133, 0x37800000, v132
	v_cndmask_b32_e32 v132, v132, v133, vcc
	v_cmp_class_f32_e32 vcc, v101, v191
	s_nop 1
	v_cndmask_b32_e32 v101, v132, v101, vcc
	v_div_scale_f32 v132, s[14:15], v101, v101, 1.0
	v_rcp_f32_e32 v133, v132
	v_div_scale_f32 v134, vcc, 1.0, v101, 1.0
	v_fma_f32 v135, -v132, v133, 1.0
	v_fmac_f32_e32 v133, v135, v133
	v_mul_f32_e32 v135, v134, v133
	v_fma_f32 v136, -v132, v135, v134
	v_fmac_f32_e32 v135, v136, v133
	v_fma_f32 v132, -v132, v135, v134
	v_div_fmas_f32 v132, v132, v133, v135
	v_div_fixup_f32 v101, v132, v101, 1.0
	v_mul_f32_e32 v44, v101, v44
	v_mul_f32_e32 v40, v101, v40
	v_mul_f32_e32 v45, v101, v45
	v_mul_f32_e32 v41, v101, v41
	v_mul_f32_e32 v46, v101, v46
; __device__ __forceinline__ unsigned pk2(float lo, float hi) { unsigned r; asm volatile("v_cvt_pk_bf16_f32 %0, %1, %2" : "=v"(r) : "v"(lo), "v"(hi)); return r; }
; __device__ __forceinline__ void rms512_inplace(bf16* __restrict__ A, int gw, int NGW, int lane) {
;     ...
;         const float rstd = 1.f / sqrtf(wave_sum(s) * (1.f / 512) + EPS_);
;         v4u o; o.x = pk2(f[0] * rstd, f[1] * rstd); o.y = pk2(f[2] * rstd, f[3] * rstd); o.z = pk2(f[4] * rstd, f[5] * rstd); o.w = pk2(f[6] * rstd, f[7] * rstd); *p = o;
	v_mul_f32_e32 v42, v101, v42
	v_mul_f32_e32 v47, v101, v47
	v_mul_f32_e32 v43, v101, v43
	v_cvt_pk_bf16_f32 v40, v44, v40
	v_cvt_pk_bf16_f32 v41, v45, v41
	v_cvt_pk_bf16_f32 v42, v46, v42
	v_cvt_pk_bf16_f32 v43, v47, v43
	global_store_dwordx4 v[118:119], v[40:43], off
	v_fmamk_f32 v102, v102, 0x3b000000, v190
	v_mul_f32_e32 v132, 0x4f800000, v102
	v_cmp_gt_f32_e32 vcc, s73, v102
	s_nop 1
	v_cndmask_b32_e32 v102, v102, v132, vcc
	v_sqrt_f32_e32 v132, v102
	s_nop 0
	v_add_u32_e32 v133, -1, v132
	v_add_u32_e32 v134, 1, v132
	v_fma_f32 v135, -v133, v132, v102
	v_fma_f32 v136, -v134, v132, v102
	v_cmp_ge_f32_e64 s[40:41], 0, v135
	s_nop 1
	v_cndmask_b32_e64 v132, v132, v133, s[40:41]
	v_cmp_lt_f32_e64 s[40:41], 0, v136
	s_nop 1
	v_cndmask_b32_e64 v132, v132, v134, s[40:41]
	v_mul_f32_e32 v133, 0x37800000, v132
	v_cndmask_b32_e32 v132, v132, v133, vcc
	v_cmp_class_f32_e32 vcc, v102, v191
	s_nop 1
	v_cndmask_b32_e32 v102, v132, v102, vcc
	v_div_scale_f32 v132, s[14:15], v102, v102, 1.0
	v_rcp_f32_e32 v133, v132
	v_div_scale_f32 v134, vcc, 1.0, v102, 1.0
	v_fma_f32 v135, -v132, v133, 1.0
	v_fmac_f32_e32 v133, v135, v133
	v_mul_f32_e32 v135, v134, v133
	v_fma_f32 v136, -v132, v135, v134
	v_fmac_f32_e32 v135, v136, v133
	v_fma_f32 v132, -v132, v135, v134
	v_div_fmas_f32 v132, v132, v133, v135
	v_div_fixup_f32 v102, v132, v102, 1.0
	v_mul_f32_e32 v52, v102, v52
	v_mul_f32_e32 v48, v102, v48
	v_mul_f32_e32 v53, v102, v53
	v_mul_f32_e32 v49, v102, v49
	v_mul_f32_e32 v54, v102, v54
	v_mul_f32_e32 v50, v102, v50
	v_mul_f32_e32 v55, v102, v55
	v_mul_f32_e32 v51, v102, v51
	v_cvt_pk_bf16_f32 v48, v52, v48
	v_cvt_pk_bf16_f32 v49, v53, v49
	v_cvt_pk_bf16_f32 v50, v54, v50
	v_cvt_pk_bf16_f32 v51, v55, v51
	global_store_dwordx4 v[120:121], v[48:51], off
	v_fmamk_f32 v103, v103, 0x3b000000, v190
	v_mul_f32_e32 v132, 0x4f800000, v103
	v_cmp_gt_f32_e32 vcc, s73, v103
	s_nop 1
	v_cndmask_b32_e32 v103, v103, v132, vcc
	v_sqrt_f32_e32 v132, v103
	s_nop 0
	v_add_u32_e32 v133, -1, v132
	v_add_u32_e32 v134, 1, v132
	v_fma_f32 v135, -v133, v132, v103
	v_fma_f32 v136, -v134, v132, v103
	v_cmp_ge_f32_e64 s[40:41], 0, v135
	s_nop 1
	v_cndmask_b32_e64 v132, v132, v133, s[40:41]
	v_cmp_lt_f32_e64 s[40:41], 0, v136
	s_nop 1
	v_cndmask_b32_e64 v132, v132, v134, s[40:41]
	v_mul_f32_e32 v133, 0x37800000, v132
	v_cndmask_b32_e32 v132, v132, v133, vcc
	v_cmp_class_f32_e32 vcc, v103, v191
	s_nop 1
	v_cndmask_b32_e32 v103, v132, v103, vcc
	v_div_scale_f32 v132, s[14:15], v103, v103, 1.0
	v_rcp_f32_e32 v133, v132
	v_div_scale_f32 v134, vcc, 1.0, v103, 1.0
	v_fma_f32 v135, -v132, v133, 1.0
	v_fmac_f32_e32 v133, v135, v133
	v_mul_f32_e32 v135, v134, v133
	v_fma_f32 v136, -v132, v135, v134
	v_fmac_f32_e32 v135, v136, v133
	v_fma_f32 v132, -v132, v135, v134
	v_div_fmas_f32 v132, v132, v133, v135
	v_div_fixup_f32 v103, v132, v103, 1.0
	v_mul_f32_e32 v60, v103, v60
	v_mul_f32_e32 v56, v103, v56
	v_mul_f32_e32 v61, v103, v61
	v_mul_f32_e32 v57, v103, v57
	v_mul_f32_e32 v62, v103, v62
	v_mul_f32_e32 v58, v103, v58
	v_mul_f32_e32 v63, v103, v63
	v_mul_f32_e32 v59, v103, v59
	v_cvt_pk_bf16_f32 v56, v60, v56
	v_cvt_pk_bf16_f32 v57, v61, v57
	v_cvt_pk_bf16_f32 v58, v62, v58
	v_cvt_pk_bf16_f32 v59, v63, v59
	global_store_dwordx4 v[122:123], v[56:59], off
	v_fmamk_f32 v104, v104, 0x3b000000, v190
	v_mul_f32_e32 v132, 0x4f800000, v104
	v_cmp_gt_f32_e32 vcc, s73, v104
	s_nop 1
	v_cndmask_b32_e32 v104, v104, v132, vcc
	v_sqrt_f32_e32 v132, v104
	s_nop 0
	v_add_u32_e32 v133, -1, v132
	v_add_u32_e32 v134, 1, v132
	v_fma_f32 v135, -v133, v132, v104
	v_fma_f32 v136, -v134, v132, v104
	v_cmp_ge_f32_e64 s[40:41], 0, v135
	s_nop 1
	v_cndmask_b32_e64 v132, v132, v133, s[40:41]
	v_cmp_lt_f32_e64 s[40:41], 0, v136
	s_nop 1
	v_cndmask_b32_e64 v132, v132, v134, s[40:41]
	v_mul_f32_e32 v133, 0x37800000, v132
	v_cndmask_b32_e32 v132, v132, v133, vcc
	v_cmp_class_f32_e32 vcc, v104, v191
	s_nop 1
	v_cndmask_b32_e32 v104, v132, v104, vcc
	v_div_scale_f32 v132, s[14:15], v104, v104, 1.0
	v_rcp_f32_e32 v133, v132
	v_div_scale_f32 v134, vcc, 1.0, v104, 1.0
	v_fma_f32 v135, -v132, v133, 1.0
	v_fmac_f32_e32 v133, v135, v133
	v_mul_f32_e32 v135, v134, v133
	v_fma_f32 v136, -v132, v135, v134
	v_fmac_f32_e32 v135, v136, v133
	v_fma_f32 v132, -v132, v135, v134
	v_div_fmas_f32 v132, v132, v133, v135
	v_div_fixup_f32 v104, v132, v104, 1.0
	v_mul_f32_e32 v68, v104, v68
	v_mul_f32_e32 v64, v104, v64
	v_mul_f32_e32 v69, v104, v69
	v_mul_f32_e32 v65, v104, v65
	v_mul_f32_e32 v70, v104, v70
	v_mul_f32_e32 v66, v104, v66
	v_mul_f32_e32 v71, v104, v71
	v_mul_f32_e32 v67, v104, v67
	v_cvt_pk_bf16_f32 v64, v68, v64
	v_cvt_pk_bf16_f32 v65, v69, v65
	v_cvt_pk_bf16_f32 v66, v70, v66
	v_cvt_pk_bf16_f32 v67, v71, v67
; __device__ __forceinline__ unsigned pk2(float lo, float hi) { unsigned r; asm volatile("v_cvt_pk_bf16_f32 %0, %1, %2" : "=v"(r) : "v"(lo), "v"(hi)); return r; }
; __device__ __forceinline__ float bflo(unsigned w) { return __uint_as_float(w << 16); }
; __device__ __forceinline__ float bfhi(unsigned w) { return __uint_as_float(w & 0xffff0000u); }
; __device__ __forceinline__ void rms512_inplace(bf16* __restrict__ A, int gw, int NGW, int lane) {
;     for (int m = gw; m < S_; m += NGW) {
;         v4u* p = (v4u*)(A + (size_t)m * 512) + lane; const v4u w = *p;
;         float f[8] = {bflo(w.x), bfhi(w.x), bflo(w.y), bfhi(w.y), bflo(w.z), bfhi(w.z), bflo(w.w), bfhi(w.w)}; float s = 0.f;
; #pragma unroll
;         for (int e = 0; e < 8; ++e) s += f[e] * f[e];
;         const float rstd = 1.f / sqrtf(wave_sum(s) * (1.f / 512) + EPS_);
;         v4u o; o.x = pk2(f[0] * rstd, f[1] * rstd); o.y = pk2(f[2] * rstd, f[3] * rstd); o.z = pk2(f[4] * rstd, f[5] * rstd); o.w = pk2(f[6] * rstd, f[7] * rstd); *p = o;
;     }
	global_store_dwordx4 v[124:125], v[64:67], off
	v_fmamk_f32 v105, v105, 0x3b000000, v190
	v_mul_f32_e32 v132, 0x4f800000, v105
	v_cmp_gt_f32_e32 vcc, s73, v105
	s_nop 1
	v_cndmask_b32_e32 v105, v105, v132, vcc
	v_sqrt_f32_e32 v132, v105
	s_nop 0
	v_add_u32_e32 v133, -1, v132
	v_add_u32_e32 v134, 1, v132
	v_fma_f32 v135, -v133, v132, v105
	v_fma_f32 v136, -v134, v132, v105
	v_cmp_ge_f32_e64 s[40:41], 0, v135
	s_nop 1
	v_cndmask_b32_e64 v132, v132, v133, s[40:41]
	v_cmp_lt_f32_e64 s[40:41], 0, v136
	s_nop 1
	v_cndmask_b32_e64 v132, v132, v134, s[40:41]
	v_mul_f32_e32 v133, 0x37800000, v132
	v_cndmask_b32_e32 v132, v132, v133, vcc
	v_cmp_class_f32_e32 vcc, v105, v191
	s_nop 1
	v_cndmask_b32_e32 v105, v132, v105, vcc
	v_div_scale_f32 v132, s[14:15], v105, v105, 1.0
	v_rcp_f32_e32 v133, v132
	v_div_scale_f32 v134, vcc, 1.0, v105, 1.0
	v_fma_f32 v135, -v132, v133, 1.0
	v_fmac_f32_e32 v133, v135, v133
	v_mul_f32_e32 v135, v134, v133
	v_fma_f32 v136, -v132, v135, v134
	v_fmac_f32_e32 v135, v136, v133
	v_fma_f32 v132, -v132, v135, v134
	v_div_fmas_f32 v132, v132, v133, v135
	v_div_fixup_f32 v105, v132, v105, 1.0
	v_mul_f32_e32 v76, v105, v76
	v_mul_f32_e32 v72, v105, v72
	v_mul_f32_e32 v77, v105, v77
	v_mul_f32_e32 v73, v105, v73
	v_mul_f32_e32 v78, v105, v78
	v_mul_f32_e32 v74, v105, v74
	v_mul_f32_e32 v79, v105, v79
	v_mul_f32_e32 v75, v105, v75
	v_cvt_pk_bf16_f32 v72, v76, v72
	v_cvt_pk_bf16_f32 v73, v77, v73
	v_cvt_pk_bf16_f32 v74, v78, v74
	v_cvt_pk_bf16_f32 v75, v79, v75
	global_store_dwordx4 v[126:127], v[72:75], off
	v_fmamk_f32 v106, v106, 0x3b000000, v190
	v_mul_f32_e32 v132, 0x4f800000, v106
	v_cmp_gt_f32_e32 vcc, s73, v106
	s_nop 1
	v_cndmask_b32_e32 v106, v106, v132, vcc
	v_sqrt_f32_e32 v132, v106
	s_nop 0
	v_add_u32_e32 v133, -1, v132
	v_add_u32_e32 v134, 1, v132
	v_fma_f32 v135, -v133, v132, v106
	v_fma_f32 v136, -v134, v132, v106
	v_cmp_ge_f32_e64 s[40:41], 0, v135
	s_nop 1
	v_cndmask_b32_e64 v132, v132, v133, s[40:41]
	v_cmp_lt_f32_e64 s[40:41], 0, v136
	s_nop 1
	v_cndmask_b32_e64 v132, v132, v134, s[40:41]
	v_mul_f32_e32 v133, 0x37800000, v132
	v_cndmask_b32_e32 v132, v132, v133, vcc
	v_cmp_class_f32_e32 vcc, v106, v191
	s_nop 1
	v_cndmask_b32_e32 v106, v132, v106, vcc
	v_div_scale_f32 v132, s[14:15], v106, v106, 1.0
	v_rcp_f32_e32 v133, v132
	v_div_scale_f32 v134, vcc, 1.0, v106, 1.0
	v_fma_f32 v135, -v132, v133, 1.0
	v_fmac_f32_e32 v133, v135, v133
	v_mul_f32_e32 v135, v134, v133
	v_fma_f32 v136, -v132, v135, v134
	v_fmac_f32_e32 v135, v136, v133
	v_fma_f32 v132, -v132, v135, v134
	v_div_fmas_f32 v132, v132, v133, v135
	v_div_fixup_f32 v106, v132, v106, 1.0
	v_mul_f32_e32 v84, v106, v84
	v_mul_f32_e32 v80, v106, v80
	v_mul_f32_e32 v85, v106, v85
	v_mul_f32_e32 v81, v106, v81
	v_mul_f32_e32 v86, v106, v86
	v_mul_f32_e32 v82, v106, v82
	v_mul_f32_e32 v87, v106, v87
	v_mul_f32_e32 v83, v106, v83
	v_cvt_pk_bf16_f32 v80, v84, v80
	v_cvt_pk_bf16_f32 v81, v85, v81
	v_cvt_pk_bf16_f32 v82, v86, v82
	v_cvt_pk_bf16_f32 v83, v87, v83
	global_store_dwordx4 v[128:129], v[80:83], off
	v_fmamk_f32 v107, v107, 0x3b000000, v190
	v_mul_f32_e32 v132, 0x4f800000, v107
	v_cmp_gt_f32_e32 vcc, s73, v107
	s_nop 1
	v_cndmask_b32_e32 v107, v107, v132, vcc
	v_sqrt_f32_e32 v132, v107
	s_nop 0
	v_add_u32_e32 v133, -1, v132
	v_add_u32_e32 v134, 1, v132
	v_fma_f32 v135, -v133, v132, v107
	v_fma_f32 v136, -v134, v132, v107
	v_cmp_ge_f32_e64 s[40:41], 0, v135
	s_nop 1
	v_cndmask_b32_e64 v132, v132, v133, s[40:41]
	v_cmp_lt_f32_e64 s[40:41], 0, v136
	s_nop 1
	v_cndmask_b32_e64 v132, v132, v134, s[40:41]
	v_mul_f32_e32 v133, 0x37800000, v132
	v_cndmask_b32_e32 v132, v132, v133, vcc
	v_cmp_class_f32_e32 vcc, v107, v191
	s_nop 1
	v_cndmask_b32_e32 v107, v132, v107, vcc
	v_div_scale_f32 v132, s[14:15], v107, v107, 1.0
	v_rcp_f32_e32 v133, v132
	v_div_scale_f32 v134, vcc, 1.0, v107, 1.0
	v_fma_f32 v135, -v132, v133, 1.0
	v_fmac_f32_e32 v133, v135, v133
	v_mul_f32_e32 v135, v134, v133
	v_fma_f32 v136, -v132, v135, v134
	v_fmac_f32_e32 v135, v136, v133
	v_fma_f32 v132, -v132, v135, v134
	v_div_fmas_f32 v132, v132, v133, v135
	v_div_fixup_f32 v107, v132, v107, 1.0
	v_mul_f32_e32 v92, v107, v92
	v_mul_f32_e32 v88, v107, v88
	v_mul_f32_e32 v93, v107, v93
	v_mul_f32_e32 v89, v107, v89
	v_mul_f32_e32 v94, v107, v94
	v_mul_f32_e32 v90, v107, v90
	v_mul_f32_e32 v95, v107, v95
	v_mul_f32_e32 v91, v107, v91
	v_cvt_pk_bf16_f32 v88, v92, v88
	v_cvt_pk_bf16_f32 v89, v93, v89
	v_cvt_pk_bf16_f32 v90, v94, v90
	v_cvt_pk_bf16_f32 v91, v95, v91
	global_store_dwordx4 v[130:131], v[88:91], off
	v_lshl_add_u64 v[2:3], v[130:131], 0, s[12:13]
	s_lshl_b32 s14, s10, 3
	s_add_i32 s5, s5, s14
	s_cmpk_lt_i32 s5, 0x4000
	s_cbranch_scc1 .Lrms_kv_batch
	s_branch .LBB0_1064
